# P0 conv-call rotation repacked so the workgroups with a third activation iteration get only 2-3 conversion calls
# baseline (speedup 1.0000x reference)
.LBB0_104:
	s_or_b64 exec, exec, s[4:5]
	v_readlane_b32 s0, v246, 1
	s_lshl_b32 s16, s0, 9
	s_mov_b32 s97, s30
	s_add_i32 s30, s97, 208
	s_and_b32 s30, s30, 0xff
	v_lshl_add_u32 v36, s30, 9, v202
	s_mov_b32 s0, 0x16000
	v_cmp_gt_i32_e64 s[4:5], s0, v36
	v_readlane_b32 s1, v246, 2
	s_and_saveexec_b64 s[6:7], s[4:5]
	s_cbranch_execz .LBB0_123
	v_readlane_b32 s36, v246, 22
	v_readlane_b32 s37, v246, 23
	s_cmp_lg_u64 s[36:37], 0
	s_cselect_b64 s[0:1], -1, 0
	v_lshlrev_b32_e32 v0, 3, v202
	v_readlane_b32 s10, v246, 1
	v_lshl_add_u32 v37, s30, 12, v0
	v_readlane_b32 s11, v246, 2
	v_cndmask_b32_e64 v0, 0, 1, s[0:1]
	s_mov_b64 s[8:9], 0
	s_lshl_b32 s10, s10, 12
	s_mov_b32 s11, 0x2e8ba2e9
	s_movk_i32 s12, 0x58
	s_movk_i32 s13, 0x2c00
	v_cmp_ne_u32_e64 s[0:1], 1, v0
	s_mov_b32 s14, 0x15fff
	v_mov_b32_e32 v38, v36
	v_readlane_b32 s38, v246, 24
	v_readlane_b32 s39, v246, 25
	v_readlane_b32 s40, v246, 26
	v_readlane_b32 s41, v246, 27
	v_readlane_b32 s42, v246, 28
	v_readlane_b32 s43, v246, 29
	v_readlane_b32 s44, v246, 30
	v_readlane_b32 s45, v246, 31
	v_readlane_b32 s46, v246, 32
	v_readlane_b32 s47, v246, 33
	v_readlane_b32 s48, v246, 34
	v_readlane_b32 s49, v246, 35
	v_readlane_b32 s50, v246, 36
	v_readlane_b32 s51, v246, 37
	s_branch .LBB0_107

.LBB0_123:
	s_or_b64 exec, exec, s[6:7]
	s_add_i32 s30, s97, 0
	s_and_b32 s30, s30, 0xff
	v_lshl_add_u32 v36, s30, 9, v202
	s_mov_b32 s0, 0x8000
	v_cmp_gt_i32_e64 s[6:7], s0, v36
	s_and_saveexec_b64 s[0:1], s[6:7]
	v_readlane_b32 s36, v246, 22
	v_readlane_b32 s46, v246, 32
	v_readlane_b32 s47, v246, 33
	v_readlane_b32 s37, v246, 23
	v_readlane_b32 s38, v246, 24
	v_readlane_b32 s39, v246, 25
	v_readlane_b32 s40, v246, 26
	v_readlane_b32 s41, v246, 27
	v_readlane_b32 s42, v246, 28
	v_readlane_b32 s43, v246, 29
	v_readlane_b32 s44, v246, 30
	v_readlane_b32 s45, v246, 31
	v_readlane_b32 s48, v246, 34
	v_readlane_b32 s49, v246, 35
	v_readlane_b32 s50, v246, 36
	v_readlane_b32 s51, v246, 37
	s_cbranch_execz .LBB0_126
	v_readlane_b32 s10, v246, 1
	s_add_u32 s8, s22, 0x580000
	v_lshlrev_b32_e32 v0, 3, v202
	v_readlane_b32 s11, v246, 2
	s_addc_u32 s9, s23, 0
	v_lshl_add_u32 v0, s30, 12, v0
	s_lshl_b32 s12, s10, 12
	s_mov_b64 s[10:11], 0
	s_movk_i32 s13, 0xffc0
	s_movk_i32 s14, 0x7fff
	v_mov_b32_e32 v1, v36

.LBB0_126:
	s_or_b64 exec, exec, s[0:1]
	s_add_i32 s30, s97, 176
	s_and_b32 s30, s30, 0xff
	v_lshl_add_u32 v36, s30, 9, v202
	s_movk_i32 s0, 0x4000
	v_cmp_gt_i32_e64 s[0:1], s0, v36
	s_and_saveexec_b64 s[10:11], s[0:1]
	s_cbranch_execz .LBB0_145
	s_add_u32 s12, s22, 0x780000
	v_readlane_b32 s36, v246, 22
	s_addc_u32 s13, s23, 0
	v_readlane_b32 s48, v246, 34
	v_readlane_b32 s49, v246, 35
	s_cmp_lg_u64 s[48:49], 0
	s_cselect_b64 s[8:9], -1, 0
	v_lshlrev_b32_e32 v0, 3, v202
	v_readlane_b32 s18, v246, 1
	v_lshl_add_u32 v37, s30, 12, v0
	v_readlane_b32 s19, v246, 2
	v_cndmask_b32_e64 v0, 0, 1, s[8:9]
	s_mov_b64 s[14:15], 0
	s_lshl_b32 s17, s18, 12
	s_movk_i32 s18, 0xffc0
	v_cmp_ne_u32_e64 s[8:9], 1, v0
	s_movk_i32 s19, 0x3fff
	v_mov_b32_e32 v38, v36
	v_readlane_b32 s37, v246, 23
	v_readlane_b32 s38, v246, 24
	v_readlane_b32 s39, v246, 25
	v_readlane_b32 s40, v246, 26
	v_readlane_b32 s41, v246, 27
	v_readlane_b32 s42, v246, 28
	v_readlane_b32 s43, v246, 29
	v_readlane_b32 s44, v246, 30
	v_readlane_b32 s45, v246, 31
	v_readlane_b32 s46, v246, 32
	v_readlane_b32 s47, v246, 33
	v_readlane_b32 s50, v246, 36
	v_readlane_b32 s51, v246, 37
	s_branch .LBB0_129

.LBB0_145:
	s_or_b64 exec, exec, s[10:11]
	s_add_i32 s30, s97, 240
	s_and_b32 s30, s30, 0xff
	v_lshl_add_u32 v36, s30, 9, v202
	s_mov_b32 s96, 0x8000
	v_cmp_gt_i32_e64 s[6:7], s96, v36
	s_and_saveexec_b64 s[8:9], s[6:7]
	s_cbranch_execz .LBB0_164
	s_add_u32 s10, s22, 0x880000
	v_readlane_b32 s36, v246, 22
	s_addc_u32 s11, s23, 0
	v_readlane_b32 s50, v246, 36
	v_readlane_b32 s51, v246, 37
	s_cmp_lg_u64 s[50:51], 0
	s_cselect_b64 s[6:7], -1, 0
	v_lshlrev_b32_e32 v0, 3, v202
	v_readlane_b32 s14, v246, 1
	v_lshl_add_u32 v37, s30, 12, v0
	v_readlane_b32 s15, v246, 2
	v_cndmask_b32_e64 v0, 0, 1, s[6:7]
	s_mov_b64 s[12:13], 0
	s_lshl_b32 s14, s14, 12
	s_movk_i32 s15, 0xffc0
	v_cmp_ne_u32_e64 s[6:7], 1, v0
	s_movk_i32 s17, 0x7fff
	v_mov_b32_e32 v38, v36
	v_readlane_b32 s37, v246, 23
	v_readlane_b32 s38, v246, 24
	v_readlane_b32 s39, v246, 25
	v_readlane_b32 s40, v246, 26
	v_readlane_b32 s41, v246, 27
	v_readlane_b32 s42, v246, 28
	v_readlane_b32 s43, v246, 29
	v_readlane_b32 s44, v246, 30
	v_readlane_b32 s45, v246, 31
	v_readlane_b32 s46, v246, 32
	v_readlane_b32 s47, v246, 33
	v_readlane_b32 s48, v246, 34
	v_readlane_b32 s49, v246, 35
	s_branch .LBB0_148

.LBB0_164:
	s_or_b64 exec, exec, s[8:9]
	s_add_i32 s30, s97, 144
	s_and_b32 s30, s30, 0xff
	v_lshl_add_u32 v36, s30, 9, v202
	s_movk_i32 s96, 0x4000
	v_cmp_gt_i32_e64 s[0:1], s96, v36
	s_and_saveexec_b64 s[6:7], s[0:1]
	v_readlane_b32 s36, v246, 38
	v_readlane_b32 s44, v246, 46
	v_readlane_b32 s45, v246, 47
	v_readlane_b32 s37, v246, 39
	v_readlane_b32 s38, v246, 40
	v_readlane_b32 s39, v246, 41
	v_readlane_b32 s40, v246, 42
	v_readlane_b32 s41, v246, 43
	v_readlane_b32 s42, v246, 44
	v_readlane_b32 s43, v246, 45
	v_readlane_b32 s46, v246, 48
	v_readlane_b32 s47, v246, 49
	v_readlane_b32 s48, v246, 50
	v_readlane_b32 s49, v246, 51
	v_readlane_b32 s50, v246, 52
	v_readlane_b32 s51, v246, 53
	s_cbranch_execz .LBB0_167
	v_readlane_b32 s8, v246, 1
	s_add_u32 s0, s22, 0xa80000
	v_lshlrev_b32_e32 v0, 3, v202
	v_readlane_b32 s9, v246, 2
	s_addc_u32 s1, s23, 0
	v_lshl_add_u32 v0, s30, 12, v0
	s_lshl_b32 s10, s8, 12
	s_mov_b64 s[8:9], 0
	s_movk_i32 s11, 0xffc0
	s_movk_i32 s12, 0x3fff
	v_mov_b32_e32 v1, v36
